# v26 + HGRN2 output unit: the three dependent shfl_xor steps of the per-row sum of squares use DPP lane movement instead of ds_bpermute
# speedup vs baseline: 1.0209x; 1.0042x over previous
; #define LAS __attribute__((address_space(3)))
; #define LDS_SYNC() do { asm volatile("s_waitcnt lgkmcnt(0)" ::: "memory"); __builtin_amdgcn_s_barrier(); asm volatile("" ::: "memory"); } while (0)
; __device__ __forceinline__ unsigned pk2(float lo, float hi) { return pg8::cvt_pk_bf16(lo, hi); }
; template <bool OUT>
; __device__ __forceinline__ void hgrn_unit(int unit, LAS unsigned char* lds, const float* HLF, const bf16* HQ, const bf16* HV, const bf16* HG, bf16* MIX, float* UBUF, float* DTOT, const float* SST, gu32* rdy4 = nullptr) {
;     ...
;             const int ti = wid & 1, vi = wid >> 1;
; #pragma unroll
;             for (int r = 0; r < 16; ++r) oacc[r] = 0.f;
; #pragma unroll
;             for (int ks = 0; ks < 4; ++ks) { const bf16x8 a = *(const LAS bf16x8*)(PP + (32 * ti + r32) * 72 + 16 * ks + 8 * hi), bb = *(const LAS bf16x8*)(VT + (32 * vi + r32) * 72 + 16 * ks + 8 * hi); oacc = MFMA32(a, bb, oacc); }
; #pragma unroll
;             for (int ks = 0; ks < 8; ++ks) { const bf16x8 a = *(const LAS bf16x8*)(QT + (32 * ti + r32) * 136 + 16 * ks + 8 * hi), bb = *(const LAS bf16x8*)(ST + (32 * vi + r32) * 136 + 16 * ks + 8 * hi); oacc = MFMA32(a, bb, oacc); }
;         }
;         {
;             float dk[16];
; #pragma unroll
;             for (int r = 0; r < 16; ++r) dk[r] = DEC[32 * ki + crow(r, hi)];
; #pragma unroll
;             for (int j = 0; j < 2; ++j)
; #pragma unroll
;                 for (int r = 0; r < 16; ++r) S[j][r] *= dk[r];
; #pragma unroll
;             for (int ks = 0; ks < 4; ++ks) { const bf16x8 a = *(const LAS bf16x8*)(KET + (32 * ki + r32) * 72 + 16 * ks + 8 * hi);
; #pragma unroll
;                 for (int j = 0; j < 2; ++j) { const bf16x8 bb = *(const LAS bf16x8*)(VT + (32 * (vi0 + j) + r32) * 72 + 16 * ks + 8 * hi); S[j] = MFMA32(a, bb, S[j]); } }
;         }
;         if (OUT) {
;             LDS_SYNC();
;             const int ti = wid & 1, vi = wid >> 1;
; #pragma unroll
;             for (int r = 0; r < 16; ++r) OS[(32 * ti + crow(r, hi)) * 132 + 32 * vi + r32] = oacc[r];
; #pragma unroll
;             for (int j = 0; j < 2; ++j)
; #pragma unroll
;                 for (int g = 0; g < 4; ++g) *(LAS v2u*)(ST + (32 * (vi0 + j) + r32) * 136 + 32 * ki + 8 * g + 4 * hi) = (v2u){pk2(S[j][4 * g], S[j][4 * g + 1]), pk2(S[j][4 * g + 2], S[j][4 * g + 3])};
;             LDS_SYNC();
.LBB0_585:
	s_waitcnt lgkmcnt(0)
	s_barrier
	ds_read_b128 v[34:37], v86
	ds_read_b128 v[38:41], v87 offset:53248
	ds_read_b128 v[98:101], v86 offset:32
	ds_read_b128 v[102:105], v87 offset:53280
	s_waitcnt lgkmcnt(2)
	v_mfma_f32_32x32x16_bf16 v[34:49], v[34:37], v[38:41], 0
	s_waitcnt lgkmcnt(0)
	v_mfma_f32_32x32x16_bf16 v[34:49], v[98:101], v[102:105], v[34:49]
	ds_read_b128 v[98:101], v86 offset:64
	ds_read_b128 v[102:105], v87 offset:53312
	ds_read_b128 v[106:109], v86 offset:96
	ds_read_b128 v[110:113], v87 offset:53344
	s_waitcnt lgkmcnt(2)
	v_mfma_f32_32x32x16_bf16 v[34:49], v[98:101], v[102:105], v[34:49]
	s_waitcnt lgkmcnt(0)
	v_mfma_f32_32x32x16_bf16 v[34:49], v[106:109], v[110:113], v[34:49]
	ds_read_b128 v[98:101], v88
	ds_read_b128 v[102:105], v89
	ds_read_b128 v[106:109], v88 offset:32
	ds_read_b128 v[110:113], v89 offset:32
	s_waitcnt lgkmcnt(2)
	v_mfma_f32_32x32x16_bf16 v[34:49], v[98:101], v[102:105], v[34:49]
	s_waitcnt lgkmcnt(0)
	v_mfma_f32_32x32x16_bf16 v[34:49], v[106:109], v[110:113], v[34:49]
	ds_read_b128 v[98:101], v88 offset:64
	ds_read_b128 v[102:105], v89 offset:64
	ds_read_b128 v[106:109], v88 offset:96
	ds_read_b128 v[110:113], v89 offset:96
	s_waitcnt lgkmcnt(2)
	v_mfma_f32_32x32x16_bf16 v[34:49], v[98:101], v[102:105], v[34:49]
	s_waitcnt lgkmcnt(0)
	v_mfma_f32_32x32x16_bf16 v[34:49], v[106:109], v[110:113], v[34:49]
	ds_read_b128 v[98:101], v88 offset:128
	ds_read_b128 v[102:105], v89 offset:128
	ds_read_b128 v[106:109], v88 offset:160
	ds_read_b128 v[110:113], v89 offset:160
	s_waitcnt lgkmcnt(2)
	v_mfma_f32_32x32x16_bf16 v[34:49], v[98:101], v[102:105], v[34:49]
	ds_read_b128 v[98:101], v88 offset:192
	ds_read_b128 v[102:105], v88 offset:224
	ds_read_b128 v[114:117], v89 offset:192
	ds_read_b128 v[118:121], v89 offset:224
	ds_read_b128 v[122:125], v90
	ds_read_b128 v[126:129], v90 offset:32
	ds_read_b128 v[130:133], v90 offset:64
	ds_read_b128 v[134:137], v90 offset:96
	s_waitcnt lgkmcnt(3)
	v_pk_mul_f32 v[2:3], v[2:3], v[122:123]
	v_pk_mul_f32 v[4:5], v[4:5], v[124:125]
	s_waitcnt lgkmcnt(2)
	v_pk_mul_f32 v[6:7], v[6:7], v[126:127]
	v_pk_mul_f32 v[8:9], v[8:9], v[128:129]
	s_waitcnt lgkmcnt(1)
	v_pk_mul_f32 v[10:11], v[10:11], v[130:131]
	v_mfma_f32_32x32x16_bf16 v[34:49], v[106:109], v[110:113], v[34:49]
	ds_read_b128 v[106:109], v91 offset:34816
	ds_read_b128 v[110:113], v91 offset:34848
	ds_read_b128 v[138:141], v92 offset:53248
	ds_read_b128 v[142:145], v92 offset:53280
	v_mul_f32_e64 v12, v12, v132
	v_mul_f32_e64 v13, v13, v133
	s_waitcnt lgkmcnt(4)
	v_pk_mul_f32 v[14:15], v[14:15], v[134:135]
	v_pk_mul_f32 v[16:17], v[16:17], v[136:137]
	v_pk_mul_f32 v[18:19], v[18:19], v[122:123]
	v_pk_mul_f32 v[20:21], v[20:21], v[124:125]
	v_pk_mul_f32 v[22:23], v[22:23], v[126:127]
	v_mfma_f32_32x32x16_bf16 v[34:49], v[98:101], v[114:117], v[34:49]
	ds_read_b128 v[98:101], v93 offset:53248
	ds_read_b128 v[114:117], v93 offset:53280
	v_mul_f32_e64 v24, v24, v128
	v_mul_f32_e64 v25, v25, v129
	v_mul_f32_e64 v26, v26, v130
	v_mul_f32_e64 v27, v27, v131
	v_pk_mul_f32 v[28:29], v[28:29], v[132:133]
	v_pk_mul_f32 v[30:31], v[30:31], v[134:135]
	v_pk_mul_f32 v[32:33], v[32:33], v[136:137]
	s_waitcnt lgkmcnt(3)
	v_mfma_f32_32x32x16_bf16 v[2:17], v[106:109], v[138:141], v[2:17]
	s_waitcnt lgkmcnt(1)
	v_mfma_f32_32x32x16_bf16 v[18:33], v[106:109], v[98:101], v[18:33]
	v_mfma_f32_32x32x16_bf16 v[2:17], v[110:113], v[142:145], v[2:17]
	s_waitcnt lgkmcnt(0)
	v_mfma_f32_32x32x16_bf16 v[18:33], v[110:113], v[114:117], v[18:33]
	ds_read_b128 v[98:101], v91 offset:34880
	ds_read_b128 v[106:109], v91 offset:34912
	ds_read_b128 v[110:113], v92 offset:53312
	ds_read_b128 v[114:117], v92 offset:53344
	ds_read_b128 v[122:125], v93 offset:53312
	ds_read_b128 v[126:129], v93 offset:53344
	s_waitcnt lgkmcnt(0)
	s_barrier
	s_waitcnt lgkmcnt(3)
	v_mfma_f32_32x32x16_bf16 v[2:17], v[98:101], v[110:113], v[2:17]
	v_mfma_f32_32x32x16_bf16 v[34:49], v[102:105], v[118:121], v[34:49]
	s_waitcnt lgkmcnt(1)
	v_mfma_f32_32x32x16_bf16 v[18:33], v[98:101], v[122:125], v[18:33]
	s_nop 9
	ds_write2_b32 v94, v34, v35 offset1:132
	v_add_u32_e32 v34, 0x400, v94
	ds_write2_b32 v34, v36, v37 offset0:8 offset1:140
	v_add_u32_e32 v34, 0x1000, v94
	ds_write2_b32 v34, v38, v39 offset0:32 offset1:164
	v_add_u32_e32 v34, 0x1400, v94
	ds_write2_b32 v34, v40, v41 offset0:40 offset1:172
	v_mfma_f32_32x32x16_bf16 v[2:17], v[106:109], v[114:117], v[2:17]
	v_add_u32_e32 v34, 0x2000, v94
	ds_write2_b32 v34, v42, v43 offset0:64 offset1:196
	v_add_u32_e32 v34, 0x2400, v94
	ds_write2_b32 v34, v44, v45 offset0:72 offset1:204
	v_add_u32_e32 v34, 0x3000, v94
	ds_write2_b32 v34, v46, v47 offset0:96 offset1:228
	v_add_u32_e32 v34, 0x3400, v94
	s_waitcnt lgkmcnt(7)
	v_mfma_f32_32x32x16_bf16 v[18:33], v[106:109], v[126:129], v[18:33]
	ds_write2_b32 v34, v48, v49 offset0:104 offset1:236
	s_nop 1
	v_cvt_pk_bf16_f32 v34, v2, v3
	v_cvt_pk_bf16_f32 v35, v4, v5
	v_cvt_pk_bf16_f32 v36, v6, v7
	v_cvt_pk_bf16_f32 v37, v8, v9
	ds_write2_b64 v95, v[34:35], v[36:37] offset1:2
	v_cvt_pk_bf16_f32 v34, v10, v11
	v_cvt_pk_bf16_f32 v35, v12, v13
	v_cvt_pk_bf16_f32 v36, v14, v15
	v_cvt_pk_bf16_f32 v37, v16, v17
	ds_write2_b64 v95, v[34:35], v[36:37] offset0:4 offset1:6
	v_cvt_pk_bf16_f32 v34, v18, v19
	v_cvt_pk_bf16_f32 v35, v20, v21
	v_cvt_pk_bf16_f32 v36, v22, v23
	v_cvt_pk_bf16_f32 v37, v24, v25
	v_add_u32_e32 v106, s58, v81
	ds_write2_b64 v96, v[34:35], v[36:37] offset1:2
	v_cvt_pk_bf16_f32 v34, v26, v27
	v_cvt_pk_bf16_f32 v35, v28, v29
	v_cvt_pk_bf16_f32 v36, v30, v31
	v_cvt_pk_bf16_f32 v37, v32, v33
	v_ashrrev_i32_e32 v107, 31, v106
	ds_write2_b64 v96, v[34:35], v[36:37] offset0:4 offset1:6
	v_lshlrev_b64 v[34:35], 10, v[106:107]
	s_waitcnt lgkmcnt(0)
	s_barrier
; __device__ __forceinline__ void store16_wt(void* p, u32x4 v) { asm volatile("global_store_dwordx4 %0, %1, off sc1\n\ts_nop 1" :: "v"(p), "v"(v) : "memory"); }
; #define LAS __attribute__((address_space(3)))
; #define LDS_SYNC() do { asm volatile("s_waitcnt lgkmcnt(0)" ::: "memory"); __builtin_amdgcn_s_barrier(); asm volatile("" ::: "memory"); } while (0)
; __device__ __forceinline__ unsigned pk2(float lo, float hi) { return pg8::cvt_pk_bf16(lo, hi); }
; template <bool OUT>
; __device__ __forceinline__ void hgrn_unit(int unit, LAS unsigned char* lds, const float* HLF, const bf16* HQ, const bf16* HV, const bf16* HG, bf16* MIX, float* UBUF, float* DTOT, const float* SST, gu32* rdy4 = nullptr) {
;     ...
;             LDS_SYNC();
;             const int t = tid >> 3, seg = tid & 7; const int row = row_base + 64 * c + t;
;             f32x4 o4[4]; float ss = 0.f;
; #pragma unroll
;             for (int i = 0; i < 4; ++i) { o4[i] = *(const LAS f32x4*)(OS + t * 132 + 16 * seg + 4 * i); ss += (o4[i][0] * o4[i][0] + o4[i][1] * o4[i][1]) + (o4[i][2] * o4[i][2] + o4[i][3] * o4[i][3]); }
;             ss += __shfl_xor(ss, 1); ss += __shfl_xor(ss, 2); ss += __shfl_xor(ss, 4);
;             const float rstd = rsqrtf(ss * (1.0f / 128.0f) + EPSF);
;             const v4u g0 = *(const v4u*)(HG + (size_t)row * 512 + col0 + 16 * seg), g1 = *(const v4u*)(HG + (size_t)row * 512 + col0 + 16 * seg + 8);
;             const unsigned gw[8] = {g0.x, g0.y, g0.z, g0.w, g1.x, g1.y, g1.z, g1.w}; unsigned ow[8];
; #pragma unroll
;             for (int i = 0; i < 8; ++i) { const float a = o4[i >> 1][2 * (i & 1)] * rstd * __builtin_bit_cast(float, gw[i] << 16), bq = o4[i >> 1][2 * (i & 1) + 1] * rstd * __builtin_bit_cast(float, gw[i] & 0xffff0000u); ow[i] = pk2(a, bq); }
;             pg8::store16_wt(MIX + (size_t)row * 1024 + 512 + col0 + 16 * seg, (v4u){ow[0], ow[1], ow[2], ow[3]}); pg8::store16_wt(MIX + (size_t)row * 1024 + 512 + col0 + 16 * seg + 8, (v4u){ow[4], ow[5], ow[6], ow[7]});
	v_lshl_add_u64 v[42:43], v[60:61], 0, v[34:35]
	ds_read_b128 v[38:41], v78
	ds_read_b128 v[46:49], v78 offset:16
	ds_read_b128 v[98:101], v78 offset:32
	ds_read_b128 v[102:105], v78 offset:48
	s_add_i32 s58, s58, 64
	s_cmpk_eq_i32 s58, 0x100
	s_waitcnt lgkmcnt(3)
	v_pk_mul_f32 v[108:109], v[40:41], v[40:41]
	v_pk_mul_f32 v[110:111], v[38:39], v[38:39]
	s_waitcnt lgkmcnt(0)
	v_mul_f32_e32 v97, v102, v102
	v_pk_mov_b32 v[112:113], v[110:111], v[108:109] op_sel:[1,0]
	v_mov_b32_e32 v111, v109
	v_pk_add_f32 v[108:109], v[112:113], v[110:111]
	v_pk_mul_f32 v[110:111], v[48:49], v[48:49]
	v_pk_mul_f32 v[112:113], v[46:47], v[46:47]
	v_pk_add_f32 v[108:109], v[108:109], v[108:109] op_sel:[0,1] op_sel_hi:[1,0]
	v_pk_mov_b32 v[114:115], v[112:113], v[110:111] op_sel:[1,0]
	v_mov_b32_e32 v113, v111
	v_pk_add_f32 v[110:111], v[114:115], v[112:113]
	v_mul_f32_e32 v112, v103, v103
	v_pk_add_f32 v[110:111], v[110:111], v[110:111] op_sel:[0,1] op_sel_hi:[1,0]
	v_mov_b32_e32 v109, v97
	v_mov_b32_e32 v111, v112
	v_pk_add_f32 v[108:109], v[108:109], v[110:111]
	v_mul_f32_e32 v110, v99, v99
	v_mul_f32_e32 v113, v104, v104
	v_pk_fma_f32 v[110:111], v[98:99], v[98:99], v[110:111] op_sel_hi:[1,1,0]
	v_mul_f32_e32 v112, v101, v101
	v_mul_f32_e32 v114, v105, v105
	v_mov_b32_e32 v111, v113
	v_pk_fma_f32 v[112:113], v[100:101], v[100:101], v[112:113] op_sel_hi:[1,1,0]
	s_nop 0
	v_mov_b32_e32 v113, v114
	v_pk_add_f32 v[110:111], v[110:111], v[112:113]
	s_nop 0
	v_pk_add_f32 v[108:109], v[108:109], v[110:111]
	s_waitcnt vmcnt(2)
	v_lshlrev_b32_e32 v110, 16, v200
	v_add_f32_e32 v97, v108, v109
	v_and_b32_e32 v109, 64, v80
	v_xor_b32_e32 v108, 1, v80
	v_add_u32_e32 v109, 64, v109
	v_cmp_lt_i32_e32 vcc, v108, v109
	v_and_b32_e32 v111, 0xffff0000, v200
	s_nop 0
	v_cndmask_b32_e32 v108, v80, v108, vcc
	v_lshlrev_b32_e32 v108, 2, v108
	v_mov_b32_dpp v108, v97 quad_perm:[1,0,3,2] row_mask:0xf bank_mask:0xf
	s_waitcnt lgkmcnt(0)
	v_add_f32_e32 v97, v97, v108
	v_xor_b32_e32 v108, 2, v80
	v_cmp_lt_i32_e32 vcc, v108, v109
	s_nop 1
	v_cndmask_b32_e32 v108, v80, v108, vcc
	v_lshlrev_b32_e32 v108, 2, v108
	v_mov_b32_dpp v108, v97 quad_perm:[2,3,0,1] row_mask:0xf bank_mask:0xf
	s_waitcnt lgkmcnt(0)
	v_add_f32_e32 v97, v97, v108
	v_xor_b32_e32 v108, 4, v80
	v_cmp_lt_i32_e32 vcc, v108, v109
	s_nop 1
	v_cndmask_b32_e32 v108, v80, v108, vcc
	v_lshlrev_b32_e32 v108, 2, v108
	v_mov_b32_dpp v108, v97 row_shr:4 row_mask:0xf bank_mask:0xa
	v_mov_b32_dpp v108, v97 row_shl:4 row_mask:0xf bank_mask:0x5
	s_waitcnt lgkmcnt(0)
	v_add_f32_e32 v97, v97, v108
	v_fmamk_f32 v97, v97, 0x3c000000, v79
	v_mul_f32_e32 v108, 0x4b800000, v97
	v_cmp_gt_f32_e32 vcc, s55, v97
	s_nop 1
	v_cndmask_b32_e32 v97, v97, v108, vcc
	v_rsq_f32_e32 v97, v97
	s_nop 0
	v_mul_f32_e32 v108, 0x45800000, v97
	v_cndmask_b32_e32 v108, v97, v108, vcc
	v_pk_mul_f32 v[38:39], v[38:39], v[108:109] op_sel_hi:[1,0]
	v_pk_mul_f32 v[40:41], v[40:41], v[108:109] op_sel_hi:[1,0]
	v_pk_mul_f32 v[38:39], v[38:39], v[110:111]
	s_nop 0
	v_cvt_pk_bf16_f32 v34, v38, v39
	v_lshlrev_b32_e32 v38, 16, v201
	v_and_b32_e32 v39, 0xffff0000, v201
	v_pk_mul_f32 v[38:39], v[40:41], v[38:39]
	v_lshlrev_b32_e32 v40, 16, v202
	v_cvt_pk_bf16_f32 v35, v38, v39
	v_pk_mul_f32 v[38:39], v[46:47], v[108:109] op_sel_hi:[1,0]
	v_and_b32_e32 v41, 0xffff0000, v202
	v_pk_mul_f32 v[38:39], v[38:39], v[40:41]
	v_lshlrev_b32_e32 v40, 16, v203
	v_cvt_pk_bf16_f32 v36, v38, v39
	v_pk_mul_f32 v[38:39], v[48:49], v[108:109] op_sel_hi:[1,0]
	v_and_b32_e32 v41, 0xffff0000, v203
	v_pk_mul_f32 v[38:39], v[38:39], v[40:41]
	s_waitcnt vmcnt(1)
	v_lshlrev_b32_e32 v40, 16, v204
	v_cvt_pk_bf16_f32 v37, v38, v39
	v_pk_mul_f32 v[38:39], v[98:99], v[108:109] op_sel_hi:[1,0]
	v_and_b32_e32 v41, 0xffff0000, v204
	v_pk_mul_f32 v[38:39], v[38:39], v[40:41]
	v_pk_mul_f32 v[40:41], v[100:101], v[108:109] op_sel_hi:[1,0]
	v_lshlrev_b32_e32 v42, 16, v205
	v_and_b32_e32 v43, 0xffff0000, v205
	v_pk_mul_f32 v[40:41], v[40:41], v[42:43]
	v_cvt_pk_bf16_f32 v38, v38, v39
	v_cvt_pk_bf16_f32 v39, v40, v41
	v_pk_mul_f32 v[40:41], v[102:103], v[108:109] op_sel_hi:[1,0]
	v_lshlrev_b32_e32 v42, 16, v206
	v_and_b32_e32 v43, 0xffff0000, v206
	v_pk_mul_f32 v[40:41], v[40:41], v[42:43]
	v_pk_mul_f32 v[42:43], v[104:105], v[108:109] op_sel_hi:[1,0]
	v_lshlrev_b32_e32 v44, 16, v207
	v_and_b32_e32 v45, 0xffff0000, v207
	v_pk_mul_f32 v[42:43], v[42:43], v[44:45]
	v_cvt_pk_bf16_f32 v40, v40, v41
	v_cvt_pk_bf16_f32 v41, v42, v43
	v_lshlrev_b64 v[42:43], 11, v[106:107]
	v_lshl_add_u64 v[42:43], s[62:63], 0, v[42:43]
	v_lshl_add_u64 v[42:43], v[42:43], 0, s[70:71]
	v_lshl_add_u64 v[42:43], v[42:43], 0, v[52:53]
	v_lshl_add_u64 v[44:45], v[42:43], 0, s[72:73]
	global_store_dwordx4 v[44:45], v[34:37], off sc1
	s_nop 1
	v_lshl_add_u64 v[34:35], v[42:43], 0, s[74:75]
	global_store_dwordx4 v[34:35], v[38:41], off sc1
	s_nop 1
	s_waitcnt lgkmcnt(0)
	s_barrier
	s_cbranch_scc1 .LBB0_596
